# baseline (speedup 1.0000x reference)
; __device__ __forceinline__ void finishSM(f32x16& p0, f32x16& p1, float alpha, float& l_reg, bf16x8& pa0, bf16x8& pa1, bf16x8& pa2, bf16x8& pa3) {
; #pragma unroll
;   for (int r = 0; r < 16; ++r) p1[r] = __builtin_amdgcn_exp2f(p1[r]);
;   float ps = 0;
; #pragma unroll
;   for (int r = 0; r < 16; ++r) ps += p0[r];
; #pragma unroll
;   for (int r = 0; r < 16; ++r) ps += p1[r];
;   { auto rr = __builtin_amdgcn_permlane32_swap(__float_as_uint(ps), __float_as_uint(ps), false, false);
;     ps = __uint_as_float(rr[0]) + __uint_as_float(rr[1]); }
;   l_reg = l_reg * alpha + ps;
;     ...
;   PK4(p0, 0, pa0); PK4(p0, 8, pa1); PK4(p1, 0, pa2); PK4(p1, 8, pa3);
; template <int BUFOFF>
; __device__ __forceinline__ void qkt_mla(f32x16& p0, f32x16& p1, const int* ka, const bf16x8* qr, const char* qlds) {
;   typedef __attribute__((address_space(3))) const bf16x8* lp;
;   p0 = f32x16{}; p1 = f32x16{};
; #pragma unroll
;   for (int d0 = 0; d0 < 12; ++d0) {
;     const int a = ka[d0 & 3] + (d0 >> 2) * 128 + BUFOFF;
;     const bf16x8 b0 = *(lp)(a), b1 = *(lp)(a + 12288);
;     bf16x8 qf;
;     qf = qr[d0];
;     p0 = __builtin_amdgcn_mfma_f32_32x32x16_bf16(b0, qf, p0, 0, 0, 0);
;     p1 = __builtin_amdgcn_mfma_f32_32x32x16_bf16(b1, qf, p1, 0, 0, 0);
;   }
; }
.LBB0_115:
	s_mov_b32 s55, s43
	s_mov_b32 s43, s52
	ds_read_b128 v[64:67], v169 offset:24576
	ds_read_b128 v[68:71], v169 offset:36864
	ds_read_b128 v[214:217], v190 offset:24576
	ds_read_b128 v[218:221], v190 offset:36864
	s_waitcnt lgkmcnt(3)
	v_mfma_f32_32x32x16_bf16 v[80:95], v[64:67], v[140:143], v[226:241]
	v_add_f32_e32 v144, v200, v145
	s_waitcnt lgkmcnt(2)
	v_mfma_f32_32x32x16_bf16 v[64:79], v[68:71], v[140:143], v[226:241]
	v_add_f32_e32 v243, v203, v210
	v_add_f32_e32 v244, v202, v208
	v_add_f32_e32 v245, v205, v212
	v_add_f32_e32 v246, v199, v211
	v_add_f32_e32 v247, v201, v213
	s_waitcnt lgkmcnt(1)
	v_mfma_f32_32x32x16_bf16 v[80:95], v[214:217], v[136:139], v[80:95]
	ds_read_b128 v[214:217], v193 offset:24576
	v_add_f32_e32 v251, v204, v207
	v_add_f32_e32 v252, v206, v209
	v_mov_b32_e32 v196, v158
	v_add_f32_e32 v144, v172, v144
	v_add_f32_e32 v243, v173, v243
	s_waitcnt lgkmcnt(1)
	v_mfma_f32_32x32x16_bf16 v[64:79], v[218:221], v[136:139], v[64:79]
	ds_read_b128 v[218:221], v193 offset:36864
	v_add_f32_e32 v244, v170, v244
	v_add_f32_e32 v245, v171, v245
	v_add_f32_e32 v246, v196, v246
	v_mov_b32_e32 v222, v147
	v_mov_b32_e32 v223, v154
	v_mov_b32_e32 v224, v155
	s_waitcnt lgkmcnt(1)
	v_mfma_f32_32x32x16_bf16 v[80:95], v[214:217], v[132:135], v[80:95]
	ds_read_b128 v[214:217], v192 offset:24576
	s_waitcnt lgkmcnt(1)
	v_mfma_f32_32x32x16_bf16 v[64:79], v[218:221], v[132:135], v[64:79]
	ds_read_b128 v[218:221], v192 offset:36864
	s_waitcnt lgkmcnt(1)
	v_mfma_f32_32x32x16_bf16 v[80:95], v[214:217], v[128:131], v[80:95]
	ds_read_b128 v[214:217], v169 offset:24704
	s_waitcnt lgkmcnt(1)
	v_mfma_f32_32x32x16_bf16 v[64:79], v[218:221], v[128:131], v[64:79]
	ds_read_b128 v[218:221], v169 offset:36992
	s_waitcnt lgkmcnt(1)
	v_mfma_f32_32x32x16_bf16 v[80:95], v[214:217], v[124:127], v[80:95]
	ds_read_b128 v[214:217], v190 offset:24704
	s_waitcnt lgkmcnt(1)
	v_mfma_f32_32x32x16_bf16 v[64:79], v[218:221], v[124:127], v[64:79]
	ds_read_b128 v[218:221], v190 offset:36992
	s_waitcnt lgkmcnt(1)
	v_mfma_f32_32x32x16_bf16 v[80:95], v[214:217], v[120:123], v[80:95]
	ds_read_b128 v[214:217], v193 offset:24704
	s_waitcnt lgkmcnt(1)
	v_mfma_f32_32x32x16_bf16 v[64:79], v[218:221], v[120:123], v[64:79]
	ds_read_b128 v[218:221], v193 offset:36992
	s_waitcnt lgkmcnt(1)
	v_mfma_f32_32x32x16_bf16 v[80:95], v[214:217], v[116:119], v[80:95]
	ds_read_b128 v[214:217], v192 offset:24704
	s_waitcnt lgkmcnt(1)
	v_mfma_f32_32x32x16_bf16 v[64:79], v[218:221], v[116:119], v[64:79]
	ds_read_b128 v[218:221], v192 offset:36992
	s_waitcnt lgkmcnt(1)
	v_mfma_f32_32x32x16_bf16 v[80:95], v[214:217], v[112:115], v[80:95]
	ds_read_b128 v[214:217], v169 offset:24832
	s_waitcnt lgkmcnt(1)
	v_mfma_f32_32x32x16_bf16 v[64:79], v[218:221], v[112:115], v[64:79]
	ds_read_b128 v[218:221], v169 offset:37120
	s_waitcnt lgkmcnt(1)
	v_mfma_f32_32x32x16_bf16 v[80:95], v[214:217], v[108:111], v[80:95]
	ds_read_b128 v[214:217], v190 offset:24832
	s_waitcnt lgkmcnt(1)
	v_mfma_f32_32x32x16_bf16 v[64:79], v[218:221], v[108:111], v[64:79]
	ds_read_b128 v[218:221], v190 offset:37120
	s_waitcnt lgkmcnt(1)
	v_mfma_f32_32x32x16_bf16 v[80:95], v[214:217], v[104:107], v[80:95]
	ds_read_b128 v[214:217], v193 offset:24832
	s_waitcnt lgkmcnt(1)
	v_mfma_f32_32x32x16_bf16 v[64:79], v[218:221], v[104:107], v[64:79]
	ds_read_b128 v[218:221], v193 offset:37120
	s_waitcnt lgkmcnt(1)
	v_mfma_f32_32x32x16_bf16 v[80:95], v[214:217], v[100:103], v[80:95]
	ds_read_b128 v[214:217], v192 offset:24832
	s_waitcnt lgkmcnt(1)
	v_mfma_f32_32x32x16_bf16 v[64:79], v[218:221], v[100:103], v[64:79]
	ds_read_b128 v[218:221], v192 offset:37120
	s_waitcnt lgkmcnt(1)
	v_mfma_f32_32x32x16_bf16 v[80:95], v[214:217], v[96:99], v[80:95]
	v_mov_b32_e32 v214, v159
	v_mov_b32_e32 v215, v152
	v_mov_b32_e32 v216, v153
	v_mov_b32_e32 v217, v150
	v_add_f32_e32 v247, v214, v247
	v_add_f32_e32 v251, v215, v251
	v_add_f32_e32 v252, v216, v252
	s_waitcnt lgkmcnt(0)
	v_mfma_f32_32x32x16_bf16 v[64:79], v[218:221], v[96:99], v[64:79]
	v_mov_b32_e32 v218, v151
	v_mov_b32_e32 v219, v148
	v_mov_b32_e32 v220, v149
	v_mov_b32_e32 v221, v146
	v_add_f32_e32 v144, v217, v144
	v_add_f32_e32 v243, v218, v243
	v_add_f32_e32 v244, v219, v244
	v_add_f32_e32 v245, v220, v245
	v_add_f32_e32 v246, v221, v246
	v_add_f32_e32 v247, v222, v247
	v_add_f32_e32 v251, v223, v251
	v_add_f32_e32 v252, v224, v252
	v_add_f32_e32 v144, v144, v243
	v_add_f32_e32 v244, v244, v245
	v_add_f32_e32 v246, v246, v247
	v_add_f32_e32 v251, v251, v252
	v_add_f32_e32 v144, v144, v244
	v_add_f32_e32 v246, v246, v251
	v_add_f32_e32 v158, v144, v246
	v_mov_b32_e32 v159, v158
	v_cvt_pk_bf16_f32 v144, v145, v210
	v_cvt_pk_bf16_f32 v145, v208, v212
	v_cvt_pk_bf16_f32 v146, v211, v213
	v_cvt_pk_bf16_f32 v147, v207, v209
	v_cvt_pk_bf16_f32 v148, v200, v203
	v_cvt_pk_bf16_f32 v149, v202, v205
	v_cvt_pk_bf16_f32 v150, v199, v201
	v_cvt_pk_bf16_f32 v151, v204, v206
	v_cvt_pk_bf16_f32 v152, v172, v173
	v_cvt_pk_bf16_f32 v153, v170, v171
	v_cvt_pk_bf16_f32 v154, v196, v214
	s_nop 1
	v_permlane32_swap_b32_e32 v158, v159
	v_cvt_pk_bf16_f32 v155, v215, v216
	v_cvt_pk_bf16_f32 v170, v217, v218
	v_cvt_pk_bf16_f32 v171, v219, v220
	v_cvt_pk_bf16_f32 v172, v221, v222
	v_cvt_pk_bf16_f32 v173, v223, v224
	v_readlane_b32 s58, v249, 37
	v_readlane_b32 s59, v249, 38
	s_add_u32 s56, s58, s47
	s_addc_u32 s57, s59, s50
	s_add_u32 s4, s56, 0x17060000
	s_addc_u32 s5, s57, 0
	s_add_u32 s58, s58, s14
	s_addc_u32 s59, s59, s15
	s_add_u32 s60, s58, 0x1a040000
	s_mov_b32 m0, s41
	s_addc_u32 s61, s59, 0
	s_lshl_b32 s52, s54, 14
	s_add_i32 s62, s40, s52
	global_load_lds_dwordx4 v188, s[4:5]
	s_mov_b32 m0, s42
	s_nop 0
	global_load_lds_dwordx4 v189, s[4:5]
	s_add_i32 m0, s41, 0x4000
	s_nop 0
	global_load_lds_dwordx4 v191, s[4:5]
	s_mov_b32 m0, s62
	s_nop 0
	global_load_lds_dwordx4 v194, s[60:61]
	s_add_i32 m0, s62, 0x2000
	s_nop 0
	global_load_lds_dwordx4 v195, s[60:61]
	s_lshl_b32 s60, s43, 14
	v_add_u32_e32 v196, s60, v167
	ds_read_b64_tr_b16 v[200:201], v196 offset:0
	ds_read_b64_tr_b16 v[202:203], v196 offset:0x800
	ds_read_b64_tr_b16 v[204:205], v196 offset:0x1000
	ds_read_b64_tr_b16 v[206:207], v196 offset:0x1800
	ds_read_b64_tr_b16 v[208:209], v196 offset:0x2000
	ds_read_b64_tr_b16 v[210:211], v196 offset:0x2800
	ds_read_b64_tr_b16 v[212:213], v196 offset:0x3000
	ds_read_b64_tr_b16 v[214:215], v196 offset:0x3800
	s_nop 0
	s_waitcnt lgkmcnt(6)
; #define SBAR() __builtin_amdgcn_sched_barrier(0)
; template <int MLA>
; __device__ __forceinline__ void partialSM(f32x16& p0, f32x16& p1, float& m_reg, float& mn, float& alpha) {
;     ...
;   float pmax = p0[0];
; #pragma unroll
;   for (int r = 1; r < 16; ++r) pmax = fmaxf(pmax, p0[r]);
; #pragma unroll
;   for (int r = 0; r < 16; ++r) pmax = fmaxf(pmax, p1[r]);
;   { auto rr = __builtin_amdgcn_permlane32_swap(__float_as_uint(pmax), __float_as_uint(pmax), false, false);
;     pmax = fmaxf(__uint_as_float(rr[0]), __uint_as_float(rr[1])); }
;   if (__builtin_expect(__all(pmax - m_reg <= THR / SCALE), 1)) { mn = m_reg; alpha = 1.f; }
;   else { mn = fmaxf(m_reg, pmax); alpha = __builtin_amdgcn_exp2f((m_reg - mn) * C); m_reg = mn; }
; template <int D0> __device__ __forceinline__ void pv_one_t(f32x16& od, int vb, bf16x8 pa0, bf16x8 pa1, bf16x8 pa2, bf16x8 pa3) {
;   const s16x4 l0 = tr_read<v_rd_off(D0, 0, 0)>(vb), h0 = tr_read<v_rd_off(D0, 0, 1)>(vb), l1 = tr_read<v_rd_off(D0, 1, 0)>(vb), h1 = tr_read<v_rd_off(D0, 1, 1)>(vb);
;   const s16x4 l2 = tr_read<v_rd_off(D0, 2, 0)>(vb), h2 = tr_read<v_rd_off(D0, 2, 1)>(vb), l3 = tr_read<v_rd_off(D0, 3, 0)>(vb), h3 = tr_read<v_rd_off(D0, 3, 1)>(vb);
;   asm volatile("s_waitcnt lgkmcnt(0)" ::: "memory"); SBAR();
;     ...
;   od = __builtin_amdgcn_mfma_f32_32x32x16_bf16(PK(l0, h0), pa0, od, 0, 0, 0);
;   od = __builtin_amdgcn_mfma_f32_32x32x16_bf16(PK(l1, h1), pa1, od, 0, 0, 0);
;   od = __builtin_amdgcn_mfma_f32_32x32x16_bf16(PK(l2, h2), pa2, od, 0, 0, 0);
;   od = __builtin_amdgcn_mfma_f32_32x32x16_bf16(PK(l3, h3), pa3, od, 0, 0, 0);
;     ...
; }
	v_mfma_f32_32x32x16_bf16 v[0:15], v[200:203], v[144:147], v[0:15]
	ds_read_b64_tr_b16 v[200:201], v196 offset:0x200
	ds_read_b64_tr_b16 v[202:203], v196 offset:0xa00
	s_waitcnt lgkmcnt(6)
	v_mfma_f32_32x32x16_bf16 v[0:15], v[204:207], v[148:151], v[0:15]
	ds_read_b64_tr_b16 v[204:205], v196 offset:0x1200
	ds_read_b64_tr_b16 v[206:207], v196 offset:0x1a00
	s_waitcnt lgkmcnt(6)
	v_mfma_f32_32x32x16_bf16 v[0:15], v[208:211], v[152:155], v[0:15]
	ds_read_b64_tr_b16 v[208:209], v196 offset:0x2200
	ds_read_b64_tr_b16 v[210:211], v196 offset:0x2a00
	s_waitcnt lgkmcnt(6)
	v_mfma_f32_32x32x16_bf16 v[0:15], v[212:215], v[170:173], v[0:15]
	ds_read_b64_tr_b16 v[212:213], v196 offset:0x3200
	ds_read_b64_tr_b16 v[214:215], v196 offset:0x3a00
	s_waitcnt lgkmcnt(6)
	v_mfma_f32_32x32x16_bf16 v[48:63], v[200:203], v[144:147], v[48:63]
	ds_read_b64_tr_b16 v[200:201], v196 offset:0x400
	ds_read_b64_tr_b16 v[202:203], v196 offset:0xc00
	s_waitcnt lgkmcnt(6)
	v_mfma_f32_32x32x16_bf16 v[48:63], v[204:207], v[148:151], v[48:63]
	ds_read_b64_tr_b16 v[204:205], v196 offset:0x1400
	ds_read_b64_tr_b16 v[206:207], v196 offset:0x1c00
	s_waitcnt lgkmcnt(6)
	v_mfma_f32_32x32x16_bf16 v[48:63], v[208:211], v[152:155], v[48:63]
	ds_read_b64_tr_b16 v[208:209], v196 offset:0x2400
	ds_read_b64_tr_b16 v[210:211], v196 offset:0x2c00
	s_waitcnt lgkmcnt(6)
	v_mfma_f32_32x32x16_bf16 v[48:63], v[212:215], v[170:173], v[48:63]
	ds_read_b64_tr_b16 v[212:213], v196 offset:0x3400
	ds_read_b64_tr_b16 v[214:215], v196 offset:0x3c00
	s_waitcnt lgkmcnt(6)
	v_mfma_f32_32x32x16_bf16 v[32:47], v[200:203], v[144:147], v[32:47]
	ds_read_b64_tr_b16 v[200:201], v196 offset:0x600
	ds_read_b64_tr_b16 v[202:203], v196 offset:0xe00
	s_waitcnt lgkmcnt(6)
	v_mfma_f32_32x32x16_bf16 v[32:47], v[204:207], v[148:151], v[32:47]
	ds_read_b64_tr_b16 v[204:205], v196 offset:0x1600
	ds_read_b64_tr_b16 v[206:207], v196 offset:0x1e00
	s_waitcnt lgkmcnt(6)
	v_mfma_f32_32x32x16_bf16 v[32:47], v[208:211], v[152:155], v[32:47]
	ds_read_b64_tr_b16 v[208:209], v196 offset:0x2600
	ds_read_b64_tr_b16 v[210:211], v196 offset:0x2e00
	s_waitcnt lgkmcnt(6)
	v_mfma_f32_32x32x16_bf16 v[32:47], v[212:215], v[170:173], v[32:47]
	ds_read_b64_tr_b16 v[212:213], v196 offset:0x3600
	ds_read_b64_tr_b16 v[214:215], v196 offset:0x3e00
	s_waitcnt lgkmcnt(6)
	v_mfma_f32_32x32x16_bf16 v[16:31], v[200:203], v[144:147], v[16:31]
	v_max_f32_e32 v144, v80, v81
	v_max3_f32 v144, v144, v82, v83
	v_max3_f32 v144, v144, v84, v85
	v_max3_f32 v144, v144, v86, v87
	v_max3_f32 v144, v144, v88, v89
	v_max3_f32 v144, v144, v90, v91
	v_max3_f32 v144, v144, v92, v93
	s_waitcnt lgkmcnt(4)
	v_mfma_f32_32x32x16_bf16 v[16:31], v[204:207], v[148:151], v[16:31]
	v_max3_f32 v144, v144, v94, v95
	v_max3_f32 v144, v144, v64, v65
	v_max3_f32 v144, v144, v66, v67
	v_max3_f32 v144, v144, v68, v69
	v_max3_f32 v144, v144, v70, v71
	v_max3_f32 v144, v144, v72, v73
	v_max3_f32 v144, v144, v74, v75
	v_max3_f32 v144, v144, v76, v77
	s_waitcnt lgkmcnt(2)
	v_mfma_f32_32x32x16_bf16 v[16:31], v[208:211], v[152:155], v[16:31]
	v_max3_f32 v144, v144, v78, v79
	v_mov_b32_e32 v145, v144
	s_nop 1
	v_permlane32_swap_b32_e32 v144, v145
	v_max_f32_e32 v144, v144, v145
	v_cmp_ge_f32_e32 vcc, s63, v144
	s_waitcnt lgkmcnt(0)
	v_mfma_f32_32x32x16_bf16 v[16:31], v[212:215], v[170:173], v[16:31]
	s_cmp_eq_u64 vcc, exec
	s_cselect_b64 s[4:5], -1, 0
	s_waitcnt vmcnt(0) lgkmcnt(0)
	s_barrier
	s_cbranch_scc1 .Lal_c_m1
	v_max_f32_e32 v242, 0, v144
	v_exp_f32_e64 v152, -v242
	s_nop 0
	v_pk_mul_f32 v[14:15], v[14:15], v[152:153] op_sel_hi:[1,0]
	v_pk_mul_f32 v[12:13], v[12:13], v[152:153] op_sel_hi:[1,0]
	v_pk_mul_f32 v[10:11], v[10:11], v[152:153] op_sel_hi:[1,0]
	v_pk_mul_f32 v[8:9], v[8:9], v[152:153] op_sel_hi:[1,0]
	v_pk_mul_f32 v[6:7], v[6:7], v[152:153] op_sel_hi:[1,0]
	v_pk_mul_f32 v[4:5], v[4:5], v[152:153] op_sel_hi:[1,0]
	v_pk_mul_f32 v[2:3], v[2:3], v[152:153] op_sel_hi:[1,0]
	v_pk_mul_f32 v[0:1], v[0:1], v[152:153] op_sel_hi:[1,0]
	v_pk_mul_f32 v[62:63], v[62:63], v[152:153] op_sel_hi:[1,0]
	v_pk_mul_f32 v[60:61], v[60:61], v[152:153] op_sel_hi:[1,0]
	v_pk_mul_f32 v[58:59], v[58:59], v[152:153] op_sel_hi:[1,0]
	v_pk_mul_f32 v[56:57], v[56:57], v[152:153] op_sel_hi:[1,0]
	v_pk_mul_f32 v[54:55], v[54:55], v[152:153] op_sel_hi:[1,0]
	v_pk_mul_f32 v[52:53], v[52:53], v[152:153] op_sel_hi:[1,0]
	v_pk_mul_f32 v[50:51], v[50:51], v[152:153] op_sel_hi:[1,0]
	v_pk_mul_f32 v[48:49], v[48:49], v[152:153] op_sel_hi:[1,0]
	v_pk_mul_f32 v[46:47], v[46:47], v[152:153] op_sel_hi:[1,0]
	v_pk_mul_f32 v[44:45], v[44:45], v[152:153] op_sel_hi:[1,0]
	v_pk_mul_f32 v[42:43], v[42:43], v[152:153] op_sel_hi:[1,0]
	v_pk_mul_f32 v[40:41], v[40:41], v[152:153] op_sel_hi:[1,0]
	v_pk_mul_f32 v[38:39], v[38:39], v[152:153] op_sel_hi:[1,0]
	v_pk_mul_f32 v[36:37], v[36:37], v[152:153] op_sel_hi:[1,0]
	v_pk_mul_f32 v[34:35], v[34:35], v[152:153] op_sel_hi:[1,0]
	v_pk_mul_f32 v[32:33], v[32:33], v[152:153] op_sel_hi:[1,0]
	v_pk_mul_f32 v[30:31], v[30:31], v[152:153] op_sel_hi:[1,0]
	v_pk_mul_f32 v[28:29], v[28:29], v[152:153] op_sel_hi:[1,0]
	v_pk_mul_f32 v[26:27], v[26:27], v[152:153] op_sel_hi:[1,0]
	v_pk_mul_f32 v[24:25], v[24:25], v[152:153] op_sel_hi:[1,0]
	v_pk_mul_f32 v[22:23], v[22:23], v[152:153] op_sel_hi:[1,0]
	v_pk_mul_f32 v[20:21], v[20:21], v[152:153] op_sel_hi:[1,0]
	v_pk_mul_f32 v[18:19], v[18:19], v[152:153] op_sel_hi:[1,0]
	v_pk_mul_f32 v[16:17], v[16:17], v[152:153] op_sel_hi:[1,0]
	v_sub_f32_e32 v80, v80, v242
	v_sub_f32_e32 v81, v81, v242
	v_sub_f32_e32 v82, v82, v242
	v_sub_f32_e32 v83, v83, v242
	v_sub_f32_e32 v84, v84, v242
	v_sub_f32_e32 v85, v85, v242
	v_sub_f32_e32 v86, v86, v242
	v_sub_f32_e32 v87, v87, v242
	v_sub_f32_e32 v88, v88, v242
	v_sub_f32_e32 v89, v89, v242
	v_sub_f32_e32 v90, v90, v242
	v_sub_f32_e32 v91, v91, v242
	v_sub_f32_e32 v92, v92, v242
	v_sub_f32_e32 v93, v93, v242
	v_sub_f32_e32 v94, v94, v242
	v_sub_f32_e32 v95, v95, v242
	v_sub_f32_e32 v64, v64, v242
	v_sub_f32_e32 v65, v65, v242
	v_sub_f32_e32 v66, v66, v242
	v_sub_f32_e32 v67, v67, v242
	v_sub_f32_e32 v68, v68, v242
	v_sub_f32_e32 v69, v69, v242
	v_sub_f32_e32 v70, v70, v242
	v_sub_f32_e32 v71, v71, v242
	v_sub_f32_e32 v72, v72, v242
	v_sub_f32_e32 v73, v73, v242
	v_sub_f32_e32 v74, v74, v242
	v_sub_f32_e32 v75, v75, v242
	v_sub_f32_e32 v76, v76, v242
	v_sub_f32_e32 v77, v77, v242
	v_sub_f32_e32 v78, v78, v242
	v_sub_f32_e32 v79, v79, v242
	v_sub_f32_e32 v226, v226, v242
	v_sub_f32_e32 v227, v227, v242
	v_sub_f32_e32 v228, v228, v242
	v_sub_f32_e32 v229, v229, v242
	v_sub_f32_e32 v230, v230, v242
	v_sub_f32_e32 v231, v231, v242
	v_sub_f32_e32 v232, v232, v242
	v_sub_f32_e32 v233, v233, v242
	v_sub_f32_e32 v234, v234, v242
	v_sub_f32_e32 v235, v235, v242
	v_sub_f32_e32 v236, v236, v242
	v_sub_f32_e32 v237, v237, v242
	v_sub_f32_e32 v238, v238, v242
	v_sub_f32_e32 v239, v239, v242
	v_sub_f32_e32 v240, v240, v242
	v_sub_f32_e32 v241, v241, v242
	s_branch .LBB0_117

; __device__ __forceinline__ void finishSM(f32x16& p0, f32x16& p1, float alpha, float& l_reg, bf16x8& pa0, bf16x8& pa1, bf16x8& pa2, bf16x8& pa3) {
; #pragma unroll
;   for (int r = 0; r < 16; ++r) p1[r] = __builtin_amdgcn_exp2f(p1[r]);
;   float ps = 0;
; #pragma unroll
;   for (int r = 0; r < 16; ++r) ps += p0[r];
; #pragma unroll
;   for (int r = 0; r < 16; ++r) ps += p1[r];
;   { auto rr = __builtin_amdgcn_permlane32_swap(__float_as_uint(ps), __float_as_uint(ps), false, false);
;     ps = __uint_as_float(rr[0]) + __uint_as_float(rr[1]); }
;   l_reg = l_reg * alpha + ps;
;     ...
;   PK4(p0, 0, pa0); PK4(p0, 8, pa1); PK4(p1, 0, pa2); PK4(p1, 8, pa3);
; template <int BUFOFF>
; __device__ __forceinline__ void qkt_mla(f32x16& p0, f32x16& p1, const int* ka, const bf16x8* qr, const char* qlds) {
;   typedef __attribute__((address_space(3))) const bf16x8* lp;
;   p0 = f32x16{}; p1 = f32x16{};
; #pragma unroll
;   for (int d0 = 0; d0 < 12; ++d0) {
;     const int a = ka[d0 & 3] + (d0 >> 2) * 128 + BUFOFF;
;     const bf16x8 b0 = *(lp)(a), b1 = *(lp)(a + 12288);
;     bf16x8 qf;
;     qf = qr[d0];
;     p0 = __builtin_amdgcn_mfma_f32_32x32x16_bf16(b0, qf, p0, 0, 0, 0);
;     p1 = __builtin_amdgcn_mfma_f32_32x32x16_bf16(b1, qf, p1, 0, 0, 0);
;   }
; }
.LBB0_117:
	v_exp_f32_e32 v155, v64
	v_exp_f32_e32 v170, v65
	v_exp_f32_e32 v171, v66
	v_exp_f32_e32 v172, v67
	v_exp_f32_e32 v173, v68
	v_exp_f32_e32 v197, v69
	v_exp_f32_e32 v199, v70
	v_exp_f32_e32 v200, v71
	v_exp_f32_e32 v201, v72
	v_exp_f32_e32 v202, v73
	v_exp_f32_e32 v203, v74
	v_exp_f32_e32 v204, v75
	v_exp_f32_e32 v205, v76
	v_exp_f32_e32 v222, v77
	v_exp_f32_e32 v223, v78
	v_exp_f32_e32 v154, v79
	v_exp_f32_e32 v206, v80
	v_exp_f32_e32 v207, v81
	v_exp_f32_e32 v208, v82
	v_exp_f32_e32 v209, v83
	v_exp_f32_e32 v210, v84
	v_exp_f32_e32 v211, v85
	v_exp_f32_e32 v212, v86
	v_exp_f32_e32 v213, v87
	v_exp_f32_e32 v214, v88
	v_exp_f32_e32 v215, v89
	v_exp_f32_e32 v216, v90
	v_exp_f32_e32 v217, v91
	v_exp_f32_e32 v218, v92
	v_exp_f32_e32 v219, v93
	v_exp_f32_e32 v220, v94
	v_exp_f32_e32 v221, v95
	ds_read_b128 v[64:67], v169
	ds_read_b128 v[68:71], v169 offset:12288
	ds_read_b128 v[144:147], v190
	ds_read_b128 v[148:151], v190 offset:12288
	v_mov_b32_e32 v224, v155
	s_waitcnt lgkmcnt(3)
	v_mfma_f32_32x32x16_bf16 v[80:95], v[64:67], v[140:143], v[226:241]
	s_waitcnt lgkmcnt(2)
	v_mfma_f32_32x32x16_bf16 v[64:79], v[68:71], v[140:143], v[226:241]
	v_mov_b32_e32 v225, v154
	s_waitcnt lgkmcnt(1)
	v_mfma_f32_32x32x16_bf16 v[80:95], v[144:147], v[136:139], v[80:95]
	ds_read_b128 v[144:147], v193
	s_waitcnt lgkmcnt(1)
	v_mfma_f32_32x32x16_bf16 v[64:79], v[148:151], v[136:139], v[64:79]
	ds_read_b128 v[148:151], v193 offset:12288
	s_waitcnt lgkmcnt(1)
	v_mfma_f32_32x32x16_bf16 v[80:95], v[144:147], v[132:135], v[80:95]
	ds_read_b128 v[144:147], v192
	s_waitcnt lgkmcnt(1)
	v_mfma_f32_32x32x16_bf16 v[64:79], v[148:151], v[132:135], v[64:79]
	ds_read_b128 v[148:151], v192 offset:12288
	s_waitcnt lgkmcnt(1)
	v_mfma_f32_32x32x16_bf16 v[80:95], v[144:147], v[128:131], v[80:95]
	ds_read_b128 v[144:147], v169 offset:128
	s_waitcnt lgkmcnt(1)
	v_mfma_f32_32x32x16_bf16 v[64:79], v[148:151], v[128:131], v[64:79]
	ds_read_b128 v[148:151], v169 offset:12416
	s_waitcnt lgkmcnt(1)
	v_mfma_f32_32x32x16_bf16 v[80:95], v[144:147], v[124:127], v[80:95]
	ds_read_b128 v[144:147], v190 offset:128
	s_waitcnt lgkmcnt(1)
	v_mfma_f32_32x32x16_bf16 v[64:79], v[148:151], v[124:127], v[64:79]
	ds_read_b128 v[148:151], v190 offset:12416
	s_waitcnt lgkmcnt(1)
	v_mfma_f32_32x32x16_bf16 v[80:95], v[144:147], v[120:123], v[80:95]
	ds_read_b128 v[144:147], v193 offset:128
	s_waitcnt lgkmcnt(1)
	v_mfma_f32_32x32x16_bf16 v[64:79], v[148:151], v[120:123], v[64:79]
	ds_read_b128 v[148:151], v193 offset:12416
	s_waitcnt lgkmcnt(1)
	v_mfma_f32_32x32x16_bf16 v[80:95], v[144:147], v[116:119], v[80:95]
	ds_read_b128 v[144:147], v192 offset:128
	s_waitcnt lgkmcnt(1)
	v_mfma_f32_32x32x16_bf16 v[64:79], v[148:151], v[116:119], v[64:79]
	ds_read_b128 v[148:151], v192 offset:12416
	s_waitcnt lgkmcnt(1)
	v_mfma_f32_32x32x16_bf16 v[80:95], v[144:147], v[112:115], v[80:95]
	ds_read_b128 v[144:147], v169 offset:256
	s_waitcnt lgkmcnt(1)
	v_mfma_f32_32x32x16_bf16 v[64:79], v[148:151], v[112:115], v[64:79]
	ds_read_b128 v[148:151], v169 offset:12544
	s_waitcnt lgkmcnt(1)
	v_mfma_f32_32x32x16_bf16 v[80:95], v[144:147], v[108:111], v[80:95]
	ds_read_b128 v[144:147], v190 offset:256
	s_waitcnt lgkmcnt(1)
	v_mfma_f32_32x32x16_bf16 v[64:79], v[148:151], v[108:111], v[64:79]
	ds_read_b128 v[148:151], v190 offset:12544
	s_waitcnt lgkmcnt(1)
	v_mfma_f32_32x32x16_bf16 v[80:95], v[144:147], v[104:107], v[80:95]
	ds_read_b128 v[144:147], v193 offset:256
	s_waitcnt lgkmcnt(1)
	v_mfma_f32_32x32x16_bf16 v[64:79], v[148:151], v[104:107], v[64:79]
	ds_read_b128 v[148:151], v193 offset:12544
	s_waitcnt lgkmcnt(1)
	v_mfma_f32_32x32x16_bf16 v[80:95], v[144:147], v[100:103], v[80:95]
	ds_read_b128 v[144:147], v192 offset:256
	s_waitcnt lgkmcnt(1)
	v_mfma_f32_32x32x16_bf16 v[64:79], v[148:151], v[100:103], v[64:79]
	ds_read_b128 v[148:151], v192 offset:12544
	s_waitcnt lgkmcnt(1)
	v_mfma_f32_32x32x16_bf16 v[80:95], v[144:147], v[96:99], v[80:95]
	v_add_f32_e32 v144, v214, v206
	v_add_f32_e32 v243, v215, v207
	v_add_f32_e32 v244, v216, v208
	v_add_f32_e32 v245, v217, v209
	v_add_f32_e32 v246, v218, v210
	v_add_f32_e32 v247, v219, v211
	v_add_f32_e32 v251, v220, v212
	v_add_f32_e32 v252, v221, v213
	v_add_f32_e32 v144, v224, v144
	v_add_f32_e32 v243, v170, v243
	v_add_f32_e32 v244, v171, v244
	v_add_f32_e32 v245, v172, v245
	v_add_f32_e32 v246, v173, v246
	v_add_f32_e32 v247, v197, v247
	v_add_f32_e32 v251, v199, v251
	v_add_f32_e32 v252, v200, v252
	v_add_f32_e32 v144, v201, v144
	v_add_f32_e32 v243, v202, v243
	s_waitcnt lgkmcnt(0)
	v_mfma_f32_32x32x16_bf16 v[64:79], v[148:151], v[96:99], v[64:79]
	v_add_f32_e32 v244, v203, v244
	v_add_f32_e32 v245, v204, v245
	v_add_f32_e32 v246, v205, v246
	v_add_f32_e32 v247, v222, v247
	v_add_f32_e32 v251, v223, v251
	v_add_f32_e32 v252, v225, v252
	v_add_f32_e32 v144, v144, v243
	v_add_f32_e32 v244, v244, v245
	v_add_f32_e32 v246, v246, v247
	v_add_f32_e32 v251, v251, v252
	v_add_f32_e32 v144, v144, v244
	v_add_f32_e32 v246, v246, v251
	v_add_f32_e32 v154, v144, v246
	v_mov_b32_e32 v155, v154
	v_cvt_pk_bf16_f32 v144, v206, v207
	v_cvt_pk_bf16_f32 v145, v208, v209
	v_cvt_pk_bf16_f32 v146, v210, v211
	v_cvt_pk_bf16_f32 v147, v212, v213
	s_nop 1
	v_permlane32_swap_b32_e32 v154, v155
	v_cvt_pk_bf16_f32 v148, v214, v215
	v_cvt_pk_bf16_f32 v149, v216, v217
	v_cvt_pk_bf16_f32 v150, v218, v219
	v_cvt_pk_bf16_f32 v151, v220, v221
	v_cvt_pk_bf16_f32 v170, v224, v170
	v_cvt_pk_bf16_f32 v171, v171, v172
	v_cvt_pk_bf16_f32 v172, v173, v197
	v_cvt_pk_bf16_f32 v173, v199, v200
	v_cvt_pk_bf16_f32 v200, v201, v202
	v_cvt_pk_bf16_f32 v201, v203, v204
	v_cvt_pk_bf16_f32 v202, v205, v222
	v_cvt_pk_bf16_f32 v203, v223, v225
	s_nop 0
	s_add_u32 s4, s56, 0x17090000
	s_addc_u32 s5, s57, 0
	s_add_u32 s56, s58, 0x1a060000
	s_mov_b32 m0, s16
	s_addc_u32 s57, s59, 0
	s_add_i32 s58, s40, s60
	global_load_lds_dwordx4 v188, s[4:5]
	s_mov_b32 m0, s17
	s_nop 0
	global_load_lds_dwordx4 v189, s[4:5]
	s_mov_b32 m0, s44
	s_nop 0
	global_load_lds_dwordx4 v191, s[4:5]
	s_mov_b32 m0, s58
	s_nop 0
	global_load_lds_dwordx4 v194, s[56:57]
	s_add_i32 m0, s58, 0x2000
	s_nop 0
	global_load_lds_dwordx4 v195, s[56:57]
	v_lshl_add_u32 v197, s55, 14, v167
	ds_read_b64_tr_b16 v[204:205], v197 offset:0
	ds_read_b64_tr_b16 v[206:207], v197 offset:0x800
	ds_read_b64_tr_b16 v[208:209], v197 offset:0x1000
	ds_read_b64_tr_b16 v[210:211], v197 offset:0x1800
	ds_read_b64_tr_b16 v[212:213], v197 offset:0x2000
	ds_read_b64_tr_b16 v[214:215], v197 offset:0x2800
	ds_read_b64_tr_b16 v[216:217], v197 offset:0x3000
	ds_read_b64_tr_b16 v[218:219], v197 offset:0x3800
	s_nop 0
	s_waitcnt lgkmcnt(6)
; #define SBAR() __builtin_amdgcn_sched_barrier(0)
; template <int MLA>
; __device__ __forceinline__ void partialSM(f32x16& p0, f32x16& p1, float& m_reg, float& mn, float& alpha) {
;     ...
;   float pmax = p0[0];
; #pragma unroll
;   for (int r = 1; r < 16; ++r) pmax = fmaxf(pmax, p0[r]);
; #pragma unroll
;   for (int r = 0; r < 16; ++r) pmax = fmaxf(pmax, p1[r]);
;   { auto rr = __builtin_amdgcn_permlane32_swap(__float_as_uint(pmax), __float_as_uint(pmax), false, false);
;     pmax = fmaxf(__uint_as_float(rr[0]), __uint_as_float(rr[1])); }
;   if (__builtin_expect(__all(pmax - m_reg <= THR / SCALE), 1)) { mn = m_reg; alpha = 1.f; }
;   else { mn = fmaxf(m_reg, pmax); alpha = __builtin_amdgcn_exp2f((m_reg - mn) * C); m_reg = mn; }
; template <int D0> __device__ __forceinline__ void pv_one_t(f32x16& od, int vb, bf16x8 pa0, bf16x8 pa1, bf16x8 pa2, bf16x8 pa3) {
;   const s16x4 l0 = tr_read<v_rd_off(D0, 0, 0)>(vb), h0 = tr_read<v_rd_off(D0, 0, 1)>(vb), l1 = tr_read<v_rd_off(D0, 1, 0)>(vb), h1 = tr_read<v_rd_off(D0, 1, 1)>(vb);
;   const s16x4 l2 = tr_read<v_rd_off(D0, 2, 0)>(vb), h2 = tr_read<v_rd_off(D0, 2, 1)>(vb), l3 = tr_read<v_rd_off(D0, 3, 0)>(vb), h3 = tr_read<v_rd_off(D0, 3, 1)>(vb);
;   asm volatile("s_waitcnt lgkmcnt(0)" ::: "memory"); SBAR();
;     ...
;   od = __builtin_amdgcn_mfma_f32_32x32x16_bf16(PK(l0, h0), pa0, od, 0, 0, 0);
;   od = __builtin_amdgcn_mfma_f32_32x32x16_bf16(PK(l1, h1), pa1, od, 0, 0, 0);
;   od = __builtin_amdgcn_mfma_f32_32x32x16_bf16(PK(l2, h2), pa2, od, 0, 0, 0);
;   od = __builtin_amdgcn_mfma_f32_32x32x16_bf16(PK(l3, h3), pa3, od, 0, 0, 0);
;     ...
; }
	v_mfma_f32_32x32x16_bf16 v[0:15], v[204:207], v[144:147], v[0:15]
	ds_read_b64_tr_b16 v[204:205], v197 offset:0x200
	ds_read_b64_tr_b16 v[206:207], v197 offset:0xa00
	s_waitcnt lgkmcnt(6)
	v_mfma_f32_32x32x16_bf16 v[0:15], v[208:211], v[148:151], v[0:15]
	ds_read_b64_tr_b16 v[208:209], v197 offset:0x1200
	ds_read_b64_tr_b16 v[210:211], v197 offset:0x1a00
	s_waitcnt lgkmcnt(6)
	v_mfma_f32_32x32x16_bf16 v[0:15], v[212:215], v[170:173], v[0:15]
	ds_read_b64_tr_b16 v[212:213], v197 offset:0x2200
	ds_read_b64_tr_b16 v[214:215], v197 offset:0x2a00
	s_waitcnt lgkmcnt(6)
	v_mfma_f32_32x32x16_bf16 v[0:15], v[216:219], v[200:203], v[0:15]
	ds_read_b64_tr_b16 v[216:217], v197 offset:0x3200
	ds_read_b64_tr_b16 v[218:219], v197 offset:0x3a00
	s_waitcnt lgkmcnt(6)
	v_mfma_f32_32x32x16_bf16 v[48:63], v[204:207], v[144:147], v[48:63]
	ds_read_b64_tr_b16 v[204:205], v197 offset:0x400
	ds_read_b64_tr_b16 v[206:207], v197 offset:0xc00
	s_waitcnt lgkmcnt(6)
	v_mfma_f32_32x32x16_bf16 v[48:63], v[208:211], v[148:151], v[48:63]
	ds_read_b64_tr_b16 v[208:209], v197 offset:0x1400
	ds_read_b64_tr_b16 v[210:211], v197 offset:0x1c00
	s_waitcnt lgkmcnt(6)
	v_mfma_f32_32x32x16_bf16 v[48:63], v[212:215], v[170:173], v[48:63]
	ds_read_b64_tr_b16 v[212:213], v197 offset:0x2400
	ds_read_b64_tr_b16 v[214:215], v197 offset:0x2c00
	s_waitcnt lgkmcnt(6)
	v_mfma_f32_32x32x16_bf16 v[48:63], v[216:219], v[200:203], v[48:63]
	ds_read_b64_tr_b16 v[216:217], v197 offset:0x3400
	ds_read_b64_tr_b16 v[218:219], v197 offset:0x3c00
	s_waitcnt lgkmcnt(6)
	v_mfma_f32_32x32x16_bf16 v[32:47], v[204:207], v[144:147], v[32:47]
	ds_read_b64_tr_b16 v[204:205], v197 offset:0x600
	ds_read_b64_tr_b16 v[206:207], v197 offset:0xe00
	s_waitcnt lgkmcnt(6)
	v_mfma_f32_32x32x16_bf16 v[32:47], v[208:211], v[148:151], v[32:47]
	ds_read_b64_tr_b16 v[208:209], v197 offset:0x1600
	ds_read_b64_tr_b16 v[210:211], v197 offset:0x1e00
	s_waitcnt lgkmcnt(6)
	v_mfma_f32_32x32x16_bf16 v[32:47], v[212:215], v[170:173], v[32:47]
	ds_read_b64_tr_b16 v[212:213], v197 offset:0x2600
	ds_read_b64_tr_b16 v[214:215], v197 offset:0x2e00
	s_waitcnt lgkmcnt(6)
	v_mfma_f32_32x32x16_bf16 v[32:47], v[216:219], v[200:203], v[32:47]
	ds_read_b64_tr_b16 v[216:217], v197 offset:0x3600
	ds_read_b64_tr_b16 v[218:219], v197 offset:0x3e00
	s_waitcnt lgkmcnt(6)
	v_mfma_f32_32x32x16_bf16 v[16:31], v[204:207], v[144:147], v[16:31]
	v_max_f32_e32 v144, v80, v81
	v_max3_f32 v144, v144, v82, v83
	v_max3_f32 v144, v144, v84, v85
	v_max3_f32 v144, v144, v86, v87
	v_max3_f32 v144, v144, v88, v89
	v_max3_f32 v144, v144, v90, v91
	v_max3_f32 v144, v144, v92, v93
	s_waitcnt lgkmcnt(4)
	v_mfma_f32_32x32x16_bf16 v[16:31], v[208:211], v[148:151], v[16:31]
	v_max3_f32 v144, v144, v94, v95
	v_max3_f32 v144, v144, v64, v65
	v_max3_f32 v144, v144, v66, v67
	v_max3_f32 v144, v144, v68, v69
	v_max3_f32 v144, v144, v70, v71
	v_max3_f32 v144, v144, v72, v73
	v_max3_f32 v144, v144, v74, v75
	v_max3_f32 v144, v144, v76, v77
	s_waitcnt lgkmcnt(2)
	v_mfma_f32_32x32x16_bf16 v[16:31], v[212:215], v[170:173], v[16:31]
	v_max3_f32 v144, v144, v78, v79
	v_mov_b32_e32 v145, v144
	s_nop 1
	v_permlane32_swap_b32_e32 v144, v145
	v_max_f32_e32 v144, v144, v145
	v_cmp_ge_f32_e32 vcc, s63, v144
	s_waitcnt lgkmcnt(0)
	v_mfma_f32_32x32x16_bf16 v[16:31], v[216:219], v[200:203], v[16:31]
	s_cmp_eq_u64 vcc, exec
	s_cselect_b64 s[4:5], -1, 0
	s_waitcnt vmcnt(0) lgkmcnt(0)
	s_barrier
	s_cbranch_scc1 .Lal_c_m2
	v_max_f32_e32 v242, 0, v144
	v_exp_f32_e64 v144, -v242
	s_nop 0
	v_pk_mul_f32 v[14:15], v[14:15], v[144:145] op_sel_hi:[1,0]
	v_pk_mul_f32 v[12:13], v[12:13], v[144:145] op_sel_hi:[1,0]
	v_pk_mul_f32 v[10:11], v[10:11], v[144:145] op_sel_hi:[1,0]
	v_pk_mul_f32 v[8:9], v[8:9], v[144:145] op_sel_hi:[1,0]
	v_pk_mul_f32 v[6:7], v[6:7], v[144:145] op_sel_hi:[1,0]
	v_pk_mul_f32 v[4:5], v[4:5], v[144:145] op_sel_hi:[1,0]
	v_pk_mul_f32 v[2:3], v[2:3], v[144:145] op_sel_hi:[1,0]
	v_pk_mul_f32 v[0:1], v[0:1], v[144:145] op_sel_hi:[1,0]
	v_pk_mul_f32 v[62:63], v[62:63], v[144:145] op_sel_hi:[1,0]
	v_pk_mul_f32 v[60:61], v[60:61], v[144:145] op_sel_hi:[1,0]
	v_pk_mul_f32 v[58:59], v[58:59], v[144:145] op_sel_hi:[1,0]
	v_pk_mul_f32 v[56:57], v[56:57], v[144:145] op_sel_hi:[1,0]
	v_pk_mul_f32 v[54:55], v[54:55], v[144:145] op_sel_hi:[1,0]
	v_pk_mul_f32 v[52:53], v[52:53], v[144:145] op_sel_hi:[1,0]
	v_pk_mul_f32 v[50:51], v[50:51], v[144:145] op_sel_hi:[1,0]
	v_pk_mul_f32 v[48:49], v[48:49], v[144:145] op_sel_hi:[1,0]
	v_pk_mul_f32 v[46:47], v[46:47], v[144:145] op_sel_hi:[1,0]
	v_pk_mul_f32 v[44:45], v[44:45], v[144:145] op_sel_hi:[1,0]
	v_pk_mul_f32 v[42:43], v[42:43], v[144:145] op_sel_hi:[1,0]
	v_pk_mul_f32 v[40:41], v[40:41], v[144:145] op_sel_hi:[1,0]
	v_pk_mul_f32 v[38:39], v[38:39], v[144:145] op_sel_hi:[1,0]
	v_pk_mul_f32 v[36:37], v[36:37], v[144:145] op_sel_hi:[1,0]
	v_pk_mul_f32 v[34:35], v[34:35], v[144:145] op_sel_hi:[1,0]
	v_pk_mul_f32 v[32:33], v[32:33], v[144:145] op_sel_hi:[1,0]
	v_pk_mul_f32 v[30:31], v[30:31], v[144:145] op_sel_hi:[1,0]
	v_pk_mul_f32 v[28:29], v[28:29], v[144:145] op_sel_hi:[1,0]
	v_pk_mul_f32 v[26:27], v[26:27], v[144:145] op_sel_hi:[1,0]
	v_pk_mul_f32 v[24:25], v[24:25], v[144:145] op_sel_hi:[1,0]
	v_pk_mul_f32 v[22:23], v[22:23], v[144:145] op_sel_hi:[1,0]
	v_pk_mul_f32 v[20:21], v[20:21], v[144:145] op_sel_hi:[1,0]
	v_pk_mul_f32 v[18:19], v[18:19], v[144:145] op_sel_hi:[1,0]
	v_pk_mul_f32 v[16:17], v[16:17], v[144:145] op_sel_hi:[1,0]
	v_sub_f32_e32 v80, v80, v242
	v_sub_f32_e32 v81, v81, v242
	v_sub_f32_e32 v82, v82, v242
	v_sub_f32_e32 v83, v83, v242
	v_sub_f32_e32 v84, v84, v242
	v_sub_f32_e32 v85, v85, v242
	v_sub_f32_e32 v86, v86, v242
	v_sub_f32_e32 v87, v87, v242
	v_sub_f32_e32 v88, v88, v242
	v_sub_f32_e32 v89, v89, v242
	v_sub_f32_e32 v90, v90, v242
	v_sub_f32_e32 v91, v91, v242
	v_sub_f32_e32 v92, v92, v242
	v_sub_f32_e32 v93, v93, v242
	v_sub_f32_e32 v94, v94, v242
	v_sub_f32_e32 v95, v95, v242
	v_sub_f32_e32 v64, v64, v242
	v_sub_f32_e32 v65, v65, v242
	v_sub_f32_e32 v66, v66, v242
	v_sub_f32_e32 v67, v67, v242
	v_sub_f32_e32 v68, v68, v242
	v_sub_f32_e32 v69, v69, v242
	v_sub_f32_e32 v70, v70, v242
	v_sub_f32_e32 v71, v71, v242
	v_sub_f32_e32 v72, v72, v242
	v_sub_f32_e32 v73, v73, v242
	v_sub_f32_e32 v74, v74, v242
	v_sub_f32_e32 v75, v75, v242
	v_sub_f32_e32 v76, v76, v242
	v_sub_f32_e32 v77, v77, v242
	v_sub_f32_e32 v78, v78, v242
	v_sub_f32_e32 v79, v79, v242
	v_sub_f32_e32 v226, v226, v242
	v_sub_f32_e32 v227, v227, v242
	v_sub_f32_e32 v228, v228, v242
	v_sub_f32_e32 v229, v229, v242
	v_sub_f32_e32 v230, v230, v242
	v_sub_f32_e32 v231, v231, v242
	v_sub_f32_e32 v232, v232, v242
	v_sub_f32_e32 v233, v233, v242
	v_sub_f32_e32 v234, v234, v242
	v_sub_f32_e32 v235, v235, v242
	v_sub_f32_e32 v236, v236, v242
	v_sub_f32_e32 v237, v237, v242
	v_sub_f32_e32 v238, v238, v242
	v_sub_f32_e32 v239, v239, v242
	v_sub_f32_e32 v240, v240, v242
	v_sub_f32_e32 v241, v241, v242
	s_branch .LBB0_119

; __device__ __forceinline__ void finishSM(f32x16& p0, f32x16& p1, float alpha, float& l_reg, bf16x8& pa0, bf16x8& pa1, bf16x8& pa2, bf16x8& pa3) {
; #pragma unroll
;   for (int r = 0; r < 16; ++r) p1[r] = __builtin_amdgcn_exp2f(p1[r]);
;   float ps = 0;
; #pragma unroll
;   for (int r = 0; r < 16; ++r) ps += p0[r];
; #pragma unroll
;   for (int r = 0; r < 16; ++r) ps += p1[r];
;   { auto rr = __builtin_amdgcn_permlane32_swap(__float_as_uint(ps), __float_as_uint(ps), false, false);
;     ps = __uint_as_float(rr[0]) + __uint_as_float(rr[1]); }
;   l_reg = l_reg * alpha + ps;
;     ...
;   PK4(p0, 0, pa0); PK4(p0, 8, pa1); PK4(p1, 0, pa2); PK4(p1, 8, pa3);
; template <int BUFOFF>
; __device__ __forceinline__ void qkt_diff(f32x16& p0, f32x16& p1, const int* ka, const bf16x8* qr) {
;   typedef __attribute__((address_space(3))) const bf16x8* lp;
;   p0 = f32x16{}; p1 = f32x16{};
; #pragma unroll
;   for (int d0 = 0; d0 < 4; ++d0) {
;     const int a = ka[d0] + BUFOFF;
;     const bf16x8 b0 = *(lp)(a), b1 = *(lp)(a + 8192);
;     p0 = __builtin_amdgcn_mfma_f32_32x32x16_bf16(b0, qr[d0], p0, 0, 0, 0);
;     p1 = __builtin_amdgcn_mfma_f32_32x32x16_bf16(b1, qr[d0], p1, 0, 0, 0);
;   }
; }
.LBB0_129:
	s_mov_b32 s54, s47
	s_mov_b32 s47, s52
	ds_read_b128 v[64:67], v138 offset:16384
	ds_read_b128 v[68:71], v138 offset:24576
	ds_read_b128 v[170:173], v141 offset:16384
	ds_read_b128 v[188:191], v141 offset:24576
	s_waitcnt lgkmcnt(3)
	v_mfma_f32_32x32x16_bf16 v[80:95], v[64:67], v[108:111], v[226:241]
	v_add_f32_e32 v112, v144, v113
	s_waitcnt lgkmcnt(2)
	v_mfma_f32_32x32x16_bf16 v[64:79], v[68:71], v[108:111], v[226:241]
	v_add_f32_e32 v243, v148, v155
	v_add_f32_e32 v244, v145, v152
	v_add_f32_e32 v245, v149, v156
	v_add_f32_e32 v246, v146, v153
	v_add_f32_e32 v247, v150, v158
	s_waitcnt lgkmcnt(1)
	v_mfma_f32_32x32x16_bf16 v[80:95], v[170:173], v[104:107], v[80:95]
	ds_read_b128 v[170:173], v140 offset:16384
	v_add_f32_e32 v251, v147, v154
	v_add_f32_e32 v252, v151, v159
	v_mov_b32_e32 v132, v124
	v_add_f32_e32 v112, v128, v112
	v_mov_b32_e32 v162, v125
	s_waitcnt lgkmcnt(1)
	v_mfma_f32_32x32x16_bf16 v[64:79], v[188:191], v[104:107], v[64:79]
	ds_read_b128 v[188:191], v140 offset:24576
	v_add_f32_e32 v243, v129, v243
	v_mov_b32_e32 v167, v120
	v_add_f32_e32 v244, v126, v244
	v_mov_b32_e32 v169, v121
	v_add_f32_e32 v245, v127, v245
	v_add_f32_e32 v246, v132, v246
	s_waitcnt lgkmcnt(1)
	v_mfma_f32_32x32x16_bf16 v[80:95], v[170:173], v[100:103], v[80:95]
	ds_read_b128 v[170:173], v139 offset:16384
	v_add_f32_e32 v247, v162, v247
	v_add_f32_e32 v251, v167, v251
	v_add_f32_e32 v252, v169, v252
	s_waitcnt lgkmcnt(1)
	v_mfma_f32_32x32x16_bf16 v[64:79], v[188:191], v[100:103], v[64:79]
	ds_read_b128 v[188:191], v139 offset:24576
	s_waitcnt lgkmcnt(1)
	v_mfma_f32_32x32x16_bf16 v[80:95], v[170:173], v[96:99], v[80:95]
	v_mov_b32_e32 v170, v118
	v_mov_b32_e32 v171, v117
	v_mov_b32_e32 v172, v114
	v_mov_b32_e32 v173, v115
	v_add_f32_e32 v112, v170, v112
	v_add_f32_e32 v243, v119, v243
	v_add_f32_e32 v244, v116, v244
	s_waitcnt lgkmcnt(0)
	v_mfma_f32_32x32x16_bf16 v[64:79], v[188:191], v[96:99], v[64:79]
	v_mov_b32_e32 v188, v122
	v_mov_b32_e32 v189, v123
	v_add_f32_e32 v245, v171, v245
	v_add_f32_e32 v246, v172, v246
	v_add_f32_e32 v247, v173, v247
	v_add_f32_e32 v251, v188, v251
	v_add_f32_e32 v252, v189, v252
	v_add_f32_e32 v112, v112, v243
	v_add_f32_e32 v244, v244, v245
	v_add_f32_e32 v246, v246, v247
	v_add_f32_e32 v251, v251, v252
	v_add_f32_e32 v112, v112, v244
	v_add_f32_e32 v246, v246, v251
	v_add_f32_e32 v117, v112, v246
	v_mov_b32_e32 v118, v117
	v_cvt_pk_bf16_f32 v112, v113, v155
	v_cvt_pk_bf16_f32 v113, v152, v156
	v_cvt_pk_bf16_f32 v114, v153, v158
	s_nop 1
	v_permlane32_swap_b32_e32 v117, v118
	v_cvt_pk_bf16_f32 v115, v154, v159
	v_cvt_pk_bf16_f32 v120, v144, v148
	v_cvt_pk_bf16_f32 v121, v145, v149
	v_cvt_pk_bf16_f32 v122, v146, v150
	v_cvt_pk_bf16_f32 v123, v147, v151
	v_cvt_pk_bf16_f32 v124, v128, v129
	v_cvt_pk_bf16_f32 v125, v126, v127
	v_cvt_pk_bf16_f32 v126, v132, v162
	v_cvt_pk_bf16_f32 v127, v167, v169
	v_cvt_pk_bf16_f32 v144, v170, v119
	v_cvt_pk_bf16_f32 v145, v116, v171
	v_cvt_pk_bf16_f32 v146, v172, v173
	v_cvt_pk_bf16_f32 v147, v188, v189
	s_add_u32 s4, s14, 0x2000000
	s_mov_b32 m0, s43
	s_addc_u32 s5, s15, 0
	s_mov_b64 s[56:57], s[14:15]
	s_lshl_b32 s52, s53, 14
	s_add_i32 s55, s42, s52
	s_nop 0
	global_load_lds_dwordx4 v134, s[56:57]
	s_mov_b32 m0, s44
	s_nop 0
	global_load_lds_dwordx4 v135, s[56:57]
	s_mov_b32 m0, s55
	s_nop 0
	global_load_lds_dwordx4 v136, s[4:5]
	s_add_i32 m0, s55, 0x2000
	s_nop 0
	global_load_lds_dwordx4 v137, s[4:5]
	s_lshl_b32 s55, s47, 14
	v_add_u32_e32 v132, s55, v133
	ds_read_b64_tr_b16 v[148:149], v132 offset:0
	ds_read_b64_tr_b16 v[150:151], v132 offset:0x800
	ds_read_b64_tr_b16 v[152:153], v132 offset:0x1000
	ds_read_b64_tr_b16 v[154:155], v132 offset:0x1800
	ds_read_b64_tr_b16 v[170:171], v132 offset:0x2000
	ds_read_b64_tr_b16 v[172:173], v132 offset:0x2800
	ds_read_b64_tr_b16 v[188:189], v132 offset:0x3000
	ds_read_b64_tr_b16 v[190:191], v132 offset:0x3800
	s_nop 0
	s_waitcnt lgkmcnt(6)
	v_mfma_f32_32x32x16_bf16 v[32:47], v[148:151], v[112:115], v[32:47]
	ds_read_b64_tr_b16 v[148:149], v132 offset:0x200
	ds_read_b64_tr_b16 v[150:151], v132 offset:0xa00
	s_waitcnt lgkmcnt(6)
	v_mfma_f32_32x32x16_bf16 v[32:47], v[152:155], v[120:123], v[32:47]
	ds_read_b64_tr_b16 v[152:153], v132 offset:0x1200
	ds_read_b64_tr_b16 v[154:155], v132 offset:0x1a00
	s_waitcnt lgkmcnt(6)
	v_mfma_f32_32x32x16_bf16 v[32:47], v[170:173], v[124:127], v[32:47]
	ds_read_b64_tr_b16 v[170:171], v132 offset:0x2200
	ds_read_b64_tr_b16 v[172:173], v132 offset:0x2a00
	s_waitcnt lgkmcnt(6)
	v_mfma_f32_32x32x16_bf16 v[32:47], v[188:191], v[144:147], v[32:47]
	ds_read_b64_tr_b16 v[188:189], v132 offset:0x3200
	ds_read_b64_tr_b16 v[190:191], v132 offset:0x3a00
	s_waitcnt lgkmcnt(6)
	v_mfma_f32_32x32x16_bf16 v[48:63], v[148:151], v[112:115], v[48:63]
	ds_read_b64_tr_b16 v[148:149], v132 offset:0x400
	ds_read_b64_tr_b16 v[150:151], v132 offset:0xc00
	s_waitcnt lgkmcnt(6)
	v_mfma_f32_32x32x16_bf16 v[48:63], v[152:155], v[120:123], v[48:63]
	ds_read_b64_tr_b16 v[152:153], v132 offset:0x1400
	ds_read_b64_tr_b16 v[154:155], v132 offset:0x1c00
	s_waitcnt lgkmcnt(6)
	v_mfma_f32_32x32x16_bf16 v[48:63], v[170:173], v[124:127], v[48:63]
	ds_read_b64_tr_b16 v[170:171], v132 offset:0x2400
	ds_read_b64_tr_b16 v[172:173], v132 offset:0x2c00
	s_waitcnt lgkmcnt(6)
	v_mfma_f32_32x32x16_bf16 v[48:63], v[188:191], v[144:147], v[48:63]
	ds_read_b64_tr_b16 v[188:189], v132 offset:0x3400
	ds_read_b64_tr_b16 v[190:191], v132 offset:0x3c00
	s_waitcnt lgkmcnt(6)
; #define SBAR() __builtin_amdgcn_sched_barrier(0)
; template <int MLA>
; __device__ __forceinline__ void partialSM(f32x16& p0, f32x16& p1, float& m_reg, float& mn, float& alpha) {
;     ...
;   float pmax = p0[0];
; #pragma unroll
;   for (int r = 1; r < 16; ++r) pmax = fmaxf(pmax, p0[r]);
; #pragma unroll
;   for (int r = 0; r < 16; ++r) pmax = fmaxf(pmax, p1[r]);
;   { auto rr = __builtin_amdgcn_permlane32_swap(__float_as_uint(pmax), __float_as_uint(pmax), false, false);
;     pmax = fmaxf(__uint_as_float(rr[0]), __uint_as_float(rr[1])); }
;   if (__builtin_expect(__all(pmax - m_reg <= THR / SCALE), 1)) { mn = m_reg; alpha = 1.f; }
;   else { mn = fmaxf(m_reg, pmax); alpha = __builtin_amdgcn_exp2f((m_reg - mn) * C); m_reg = mn; }
; template <int D0> __device__ __forceinline__ void pv_one_t(f32x16& od, int vb, bf16x8 pa0, bf16x8 pa1, bf16x8 pa2, bf16x8 pa3) {
;   const s16x4 l0 = tr_read<v_rd_off(D0, 0, 0)>(vb), h0 = tr_read<v_rd_off(D0, 0, 1)>(vb), l1 = tr_read<v_rd_off(D0, 1, 0)>(vb), h1 = tr_read<v_rd_off(D0, 1, 1)>(vb);
;   const s16x4 l2 = tr_read<v_rd_off(D0, 2, 0)>(vb), h2 = tr_read<v_rd_off(D0, 2, 1)>(vb), l3 = tr_read<v_rd_off(D0, 3, 0)>(vb), h3 = tr_read<v_rd_off(D0, 3, 1)>(vb);
;   asm volatile("s_waitcnt lgkmcnt(0)" ::: "memory"); SBAR();
;     ...
;   od = __builtin_amdgcn_mfma_f32_32x32x16_bf16(PK(l0, h0), pa0, od, 0, 0, 0);
;   od = __builtin_amdgcn_mfma_f32_32x32x16_bf16(PK(l1, h1), pa1, od, 0, 0, 0);
;   od = __builtin_amdgcn_mfma_f32_32x32x16_bf16(PK(l2, h2), pa2, od, 0, 0, 0);
;   od = __builtin_amdgcn_mfma_f32_32x32x16_bf16(PK(l3, h3), pa3, od, 0, 0, 0);
;     ...
; }
	v_mfma_f32_32x32x16_bf16 v[16:31], v[148:151], v[112:115], v[16:31]
	ds_read_b64_tr_b16 v[148:149], v132 offset:0x600
	ds_read_b64_tr_b16 v[150:151], v132 offset:0xe00
	s_waitcnt lgkmcnt(6)
	v_mfma_f32_32x32x16_bf16 v[16:31], v[152:155], v[120:123], v[16:31]
	ds_read_b64_tr_b16 v[152:153], v132 offset:0x1600
	ds_read_b64_tr_b16 v[154:155], v132 offset:0x1e00
	s_waitcnt lgkmcnt(6)
	v_mfma_f32_32x32x16_bf16 v[16:31], v[170:173], v[124:127], v[16:31]
	ds_read_b64_tr_b16 v[170:171], v132 offset:0x2600
	ds_read_b64_tr_b16 v[172:173], v132 offset:0x2e00
	s_waitcnt lgkmcnt(6)
	v_mfma_f32_32x32x16_bf16 v[16:31], v[188:191], v[144:147], v[16:31]
	ds_read_b64_tr_b16 v[188:189], v132 offset:0x3600
	ds_read_b64_tr_b16 v[190:191], v132 offset:0x3e00
	s_waitcnt lgkmcnt(6)
	v_mfma_f32_32x32x16_bf16 v[0:15], v[148:151], v[112:115], v[0:15]
	v_max_f32_e32 v112, v80, v81
	v_max3_f32 v112, v112, v82, v83
	v_max3_f32 v112, v112, v84, v85
	v_max3_f32 v112, v112, v86, v87
	v_max3_f32 v112, v112, v88, v89
	v_max3_f32 v112, v112, v90, v91
	v_max3_f32 v112, v112, v92, v93
	s_waitcnt lgkmcnt(4)
	v_mfma_f32_32x32x16_bf16 v[0:15], v[152:155], v[120:123], v[0:15]
	v_max3_f32 v112, v112, v94, v95
	v_max3_f32 v112, v112, v64, v65
	v_max3_f32 v112, v112, v66, v67
	v_max3_f32 v112, v112, v68, v69
	v_max3_f32 v112, v112, v70, v71
	v_max3_f32 v112, v112, v72, v73
	v_max3_f32 v112, v112, v74, v75
	v_max3_f32 v112, v112, v76, v77
	s_waitcnt lgkmcnt(2)
	v_mfma_f32_32x32x16_bf16 v[0:15], v[170:173], v[124:127], v[0:15]
	v_max3_f32 v112, v112, v78, v79
	v_mov_b32_e32 v113, v112
	s_nop 1
	v_permlane32_swap_b32_e32 v112, v113
	v_max_f32_e32 v112, v112, v113
	v_cmp_ge_f32_e32 vcc, s70, v112
	s_waitcnt lgkmcnt(0)
	v_mfma_f32_32x32x16_bf16 v[0:15], v[188:191], v[144:147], v[0:15]
	s_cmp_eq_u64 vcc, exec
	s_cselect_b64 s[4:5], -1, 0
	s_waitcnt vmcnt(0) lgkmcnt(0)
	s_barrier
	s_cbranch_scc1 .Lal_c_d1
	v_max_f32_e32 v242, 0, v112
	v_exp_f32_e64 v116, -v242
	s_nop 0
	v_pk_mul_f32 v[46:47], v[46:47], v[116:117] op_sel_hi:[1,0]
	v_pk_mul_f32 v[44:45], v[44:45], v[116:117] op_sel_hi:[1,0]
	v_pk_mul_f32 v[42:43], v[42:43], v[116:117] op_sel_hi:[1,0]
	v_pk_mul_f32 v[40:41], v[40:41], v[116:117] op_sel_hi:[1,0]
	v_pk_mul_f32 v[38:39], v[38:39], v[116:117] op_sel_hi:[1,0]
	v_pk_mul_f32 v[36:37], v[36:37], v[116:117] op_sel_hi:[1,0]
	v_pk_mul_f32 v[34:35], v[34:35], v[116:117] op_sel_hi:[1,0]
	v_pk_mul_f32 v[32:33], v[32:33], v[116:117] op_sel_hi:[1,0]
	v_pk_mul_f32 v[62:63], v[62:63], v[116:117] op_sel_hi:[1,0]
	v_pk_mul_f32 v[60:61], v[60:61], v[116:117] op_sel_hi:[1,0]
	v_pk_mul_f32 v[58:59], v[58:59], v[116:117] op_sel_hi:[1,0]
	v_pk_mul_f32 v[56:57], v[56:57], v[116:117] op_sel_hi:[1,0]
	v_pk_mul_f32 v[54:55], v[54:55], v[116:117] op_sel_hi:[1,0]
	v_pk_mul_f32 v[52:53], v[52:53], v[116:117] op_sel_hi:[1,0]
	v_pk_mul_f32 v[50:51], v[50:51], v[116:117] op_sel_hi:[1,0]
	v_pk_mul_f32 v[48:49], v[48:49], v[116:117] op_sel_hi:[1,0]
	v_pk_mul_f32 v[30:31], v[30:31], v[116:117] op_sel_hi:[1,0]
	v_pk_mul_f32 v[28:29], v[28:29], v[116:117] op_sel_hi:[1,0]
	v_pk_mul_f32 v[26:27], v[26:27], v[116:117] op_sel_hi:[1,0]
	v_pk_mul_f32 v[24:25], v[24:25], v[116:117] op_sel_hi:[1,0]
	v_pk_mul_f32 v[22:23], v[22:23], v[116:117] op_sel_hi:[1,0]
	v_pk_mul_f32 v[20:21], v[20:21], v[116:117] op_sel_hi:[1,0]
	v_pk_mul_f32 v[18:19], v[18:19], v[116:117] op_sel_hi:[1,0]
	v_pk_mul_f32 v[16:17], v[16:17], v[116:117] op_sel_hi:[1,0]
	v_pk_mul_f32 v[14:15], v[14:15], v[116:117] op_sel_hi:[1,0]
	v_pk_mul_f32 v[12:13], v[12:13], v[116:117] op_sel_hi:[1,0]
	v_pk_mul_f32 v[10:11], v[10:11], v[116:117] op_sel_hi:[1,0]
	v_pk_mul_f32 v[8:9], v[8:9], v[116:117] op_sel_hi:[1,0]
	v_pk_mul_f32 v[6:7], v[6:7], v[116:117] op_sel_hi:[1,0]
	v_pk_mul_f32 v[4:5], v[4:5], v[116:117] op_sel_hi:[1,0]
	v_pk_mul_f32 v[2:3], v[2:3], v[116:117] op_sel_hi:[1,0]
	v_pk_mul_f32 v[0:1], v[0:1], v[116:117] op_sel_hi:[1,0]
	v_sub_f32_e32 v80, v80, v242
	v_sub_f32_e32 v81, v81, v242
	v_sub_f32_e32 v82, v82, v242
	v_sub_f32_e32 v83, v83, v242
	v_sub_f32_e32 v84, v84, v242
	v_sub_f32_e32 v85, v85, v242
	v_sub_f32_e32 v86, v86, v242
	v_sub_f32_e32 v87, v87, v242
	v_sub_f32_e32 v88, v88, v242
	v_sub_f32_e32 v89, v89, v242
	v_sub_f32_e32 v90, v90, v242
	v_sub_f32_e32 v91, v91, v242
	v_sub_f32_e32 v92, v92, v242
	v_sub_f32_e32 v93, v93, v242
	v_sub_f32_e32 v94, v94, v242
	v_sub_f32_e32 v95, v95, v242
	v_sub_f32_e32 v64, v64, v242
	v_sub_f32_e32 v65, v65, v242
	v_sub_f32_e32 v66, v66, v242
	v_sub_f32_e32 v67, v67, v242
	v_sub_f32_e32 v68, v68, v242
	v_sub_f32_e32 v69, v69, v242
	v_sub_f32_e32 v70, v70, v242
	v_sub_f32_e32 v71, v71, v242
	v_sub_f32_e32 v72, v72, v242
	v_sub_f32_e32 v73, v73, v242
	v_sub_f32_e32 v74, v74, v242
	v_sub_f32_e32 v75, v75, v242
	v_sub_f32_e32 v76, v76, v242
	v_sub_f32_e32 v77, v77, v242
	v_sub_f32_e32 v78, v78, v242
	v_sub_f32_e32 v79, v79, v242
	v_sub_f32_e32 v226, v226, v242
	v_sub_f32_e32 v227, v227, v242
	v_sub_f32_e32 v228, v228, v242
	v_sub_f32_e32 v229, v229, v242
	v_sub_f32_e32 v230, v230, v242
	v_sub_f32_e32 v231, v231, v242
	v_sub_f32_e32 v232, v232, v242
	v_sub_f32_e32 v233, v233, v242
	v_sub_f32_e32 v234, v234, v242
	v_sub_f32_e32 v235, v235, v242
	v_sub_f32_e32 v236, v236, v242
	v_sub_f32_e32 v237, v237, v242
	v_sub_f32_e32 v238, v238, v242
	v_sub_f32_e32 v239, v239, v242
	v_sub_f32_e32 v240, v240, v242
	v_sub_f32_e32 v241, v241, v242
	s_branch .LBB0_131

; __device__ __forceinline__ void finishSM(f32x16& p0, f32x16& p1, float alpha, float& l_reg, bf16x8& pa0, bf16x8& pa1, bf16x8& pa2, bf16x8& pa3) {
; #pragma unroll
;   for (int r = 0; r < 16; ++r) p1[r] = __builtin_amdgcn_exp2f(p1[r]);
;   float ps = 0;
; #pragma unroll
;   for (int r = 0; r < 16; ++r) ps += p0[r];
; #pragma unroll
;   for (int r = 0; r < 16; ++r) ps += p1[r];
;   { auto rr = __builtin_amdgcn_permlane32_swap(__float_as_uint(ps), __float_as_uint(ps), false, false);
;     ps = __uint_as_float(rr[0]) + __uint_as_float(rr[1]); }
;   l_reg = l_reg * alpha + ps;
;     ...
;   PK4(p0, 0, pa0); PK4(p0, 8, pa1); PK4(p1, 0, pa2); PK4(p1, 8, pa3);
; template <int BUFOFF>
; __device__ __forceinline__ void qkt_diff(f32x16& p0, f32x16& p1, const int* ka, const bf16x8* qr) {
;   typedef __attribute__((address_space(3))) const bf16x8* lp;
;   p0 = f32x16{}; p1 = f32x16{};
; #pragma unroll
;   for (int d0 = 0; d0 < 4; ++d0) {
;     const int a = ka[d0] + BUFOFF;
;     const bf16x8 b0 = *(lp)(a), b1 = *(lp)(a + 8192);
;     p0 = __builtin_amdgcn_mfma_f32_32x32x16_bf16(b0, qr[d0], p0, 0, 0, 0);
;     p1 = __builtin_amdgcn_mfma_f32_32x32x16_bf16(b1, qr[d0], p1, 0, 0, 0);
;   }
; }
.LBB0_131:
	v_exp_f32_e32 v125, v64
	v_exp_f32_e32 v126, v65
	v_exp_f32_e32 v127, v66
	v_exp_f32_e32 v128, v67
	v_exp_f32_e32 v129, v68
	v_exp_f32_e32 v143, v69
	v_exp_f32_e32 v144, v70
	v_exp_f32_e32 v145, v71
	v_exp_f32_e32 v146, v72
	v_exp_f32_e32 v147, v73
	v_exp_f32_e32 v148, v74
	v_exp_f32_e32 v149, v75
	v_exp_f32_e32 v150, v76
	v_exp_f32_e32 v151, v80
	v_exp_f32_e32 v152, v81
	v_exp_f32_e32 v153, v82
	v_exp_f32_e32 v154, v83
	v_exp_f32_e32 v155, v84
	v_exp_f32_e32 v156, v85
	v_exp_f32_e32 v158, v86
	v_exp_f32_e32 v159, v87
	v_exp_f32_e32 v162, v88
	v_exp_f32_e32 v167, v89
	v_exp_f32_e32 v169, v90
	v_exp_f32_e32 v170, v91
	v_exp_f32_e32 v171, v92
	v_exp_f32_e32 v172, v93
	v_exp_f32_e32 v173, v94
	v_exp_f32_e32 v188, v95
	v_exp_f32_e32 v189, v77
	v_exp_f32_e32 v190, v78
	v_exp_f32_e32 v124, v79
	ds_read_b128 v[64:67], v138
	ds_read_b128 v[68:71], v138 offset:8192
	ds_read_b128 v[112:115], v141
	ds_read_b128 v[120:123], v141 offset:8192
	v_mov_b32_e32 v191, v125
	s_waitcnt lgkmcnt(3)
	v_mfma_f32_32x32x16_bf16 v[80:95], v[64:67], v[108:111], v[226:241]
	s_waitcnt lgkmcnt(2)
	v_mfma_f32_32x32x16_bf16 v[64:79], v[68:71], v[108:111], v[226:241]
	v_mov_b32_e32 v192, v124
	s_waitcnt lgkmcnt(1)
	v_mfma_f32_32x32x16_bf16 v[80:95], v[112:115], v[104:107], v[80:95]
	ds_read_b128 v[112:115], v140
	s_waitcnt lgkmcnt(1)
	v_mfma_f32_32x32x16_bf16 v[64:79], v[120:123], v[104:107], v[64:79]
	ds_read_b128 v[120:123], v140 offset:8192
	s_waitcnt lgkmcnt(1)
	v_mfma_f32_32x32x16_bf16 v[80:95], v[112:115], v[100:103], v[80:95]
	ds_read_b128 v[112:115], v139
	s_waitcnt lgkmcnt(1)
	v_mfma_f32_32x32x16_bf16 v[64:79], v[120:123], v[100:103], v[64:79]
	ds_read_b128 v[120:123], v139 offset:8192
	s_waitcnt lgkmcnt(1)
	v_mfma_f32_32x32x16_bf16 v[80:95], v[112:115], v[96:99], v[80:95]
	v_add_f32_e32 v112, v162, v151
	v_add_f32_e32 v243, v167, v152
	v_add_f32_e32 v244, v169, v153
	v_add_f32_e32 v245, v170, v154
	v_add_f32_e32 v246, v171, v155
	v_add_f32_e32 v247, v172, v156
	v_add_f32_e32 v251, v173, v158
	v_add_f32_e32 v252, v188, v159
	v_add_f32_e32 v112, v191, v112
	v_add_f32_e32 v243, v126, v243
	v_add_f32_e32 v244, v127, v244
	v_add_f32_e32 v245, v128, v245
	v_add_f32_e32 v246, v129, v246
	v_add_f32_e32 v247, v143, v247
	v_add_f32_e32 v251, v144, v251
	v_add_f32_e32 v252, v145, v252
	v_add_f32_e32 v112, v146, v112
	v_add_f32_e32 v243, v147, v243
	s_waitcnt lgkmcnt(0)
	v_mfma_f32_32x32x16_bf16 v[64:79], v[120:123], v[96:99], v[64:79]
	v_add_f32_e32 v244, v148, v244
	v_add_f32_e32 v245, v149, v245
	v_add_f32_e32 v246, v150, v246
	v_add_f32_e32 v247, v189, v247
	v_add_f32_e32 v251, v190, v251
	v_add_f32_e32 v252, v192, v252
	v_add_f32_e32 v112, v112, v243
	v_add_f32_e32 v244, v244, v245
	v_add_f32_e32 v246, v246, v247
	v_add_f32_e32 v251, v251, v252
	v_add_f32_e32 v112, v112, v244
	v_add_f32_e32 v246, v246, v251
	v_add_f32_e32 v120, v112, v246
	v_mov_b32_e32 v121, v120
	v_cvt_pk_bf16_f32 v112, v151, v152
	v_cvt_pk_bf16_f32 v113, v153, v154
	v_cvt_pk_bf16_f32 v114, v155, v156
	v_cvt_pk_bf16_f32 v115, v158, v159
	s_nop 1
	v_permlane32_swap_b32_e32 v120, v121
	v_cvt_pk_bf16_f32 v122, v162, v167
	v_cvt_pk_bf16_f32 v123, v169, v170
	v_cvt_pk_bf16_f32 v124, v171, v172
	v_cvt_pk_bf16_f32 v125, v173, v188
	v_cvt_pk_bf16_f32 v126, v191, v126
	v_cvt_pk_bf16_f32 v127, v127, v128
	v_cvt_pk_bf16_f32 v128, v129, v143
	v_cvt_pk_bf16_f32 v129, v144, v145
	v_cvt_pk_bf16_f32 v144, v146, v147
	v_cvt_pk_bf16_f32 v145, v148, v149
	v_cvt_pk_bf16_f32 v146, v150, v189
	v_cvt_pk_bf16_f32 v147, v190, v192
	s_nop 0
	s_add_u32 s4, s14, 0x20000
	s_addc_u32 s5, s15, 0
	s_add_u32 s56, s14, 0x2020000
	s_mov_b32 m0, s16
	s_addc_u32 s57, s15, 0
	s_add_i32 s55, s42, s55
	s_nop 0
	global_load_lds_dwordx4 v134, s[4:5]
	s_mov_b32 m0, s17
	s_nop 0
	global_load_lds_dwordx4 v135, s[4:5]
	s_mov_b32 m0, s55
	s_nop 0
	global_load_lds_dwordx4 v136, s[56:57]
	s_add_i32 m0, s55, 0x2000
	s_nop 0
	global_load_lds_dwordx4 v137, s[56:57]
	v_lshl_add_u32 v143, s54, 14, v133
	ds_read_b64_tr_b16 v[148:149], v143 offset:0
	ds_read_b64_tr_b16 v[150:151], v143 offset:0x800
	ds_read_b64_tr_b16 v[152:153], v143 offset:0x1000
	ds_read_b64_tr_b16 v[154:155], v143 offset:0x1800
	ds_read_b64_tr_b16 v[170:171], v143 offset:0x2000
	ds_read_b64_tr_b16 v[172:173], v143 offset:0x2800
	ds_read_b64_tr_b16 v[188:189], v143 offset:0x3000
	ds_read_b64_tr_b16 v[190:191], v143 offset:0x3800
	s_nop 0
	s_waitcnt lgkmcnt(6)
	v_mfma_f32_32x32x16_bf16 v[32:47], v[148:151], v[112:115], v[32:47]
	ds_read_b64_tr_b16 v[148:149], v143 offset:0x200
	ds_read_b64_tr_b16 v[150:151], v143 offset:0xa00
	s_waitcnt lgkmcnt(6)
	v_mfma_f32_32x32x16_bf16 v[32:47], v[152:155], v[122:125], v[32:47]
	ds_read_b64_tr_b16 v[152:153], v143 offset:0x1200
	ds_read_b64_tr_b16 v[154:155], v143 offset:0x1a00
	s_waitcnt lgkmcnt(6)
	v_mfma_f32_32x32x16_bf16 v[32:47], v[170:173], v[126:129], v[32:47]
	ds_read_b64_tr_b16 v[170:171], v143 offset:0x2200
	ds_read_b64_tr_b16 v[172:173], v143 offset:0x2a00
	s_waitcnt lgkmcnt(6)
	v_mfma_f32_32x32x16_bf16 v[32:47], v[188:191], v[144:147], v[32:47]
	ds_read_b64_tr_b16 v[188:189], v143 offset:0x3200
	ds_read_b64_tr_b16 v[190:191], v143 offset:0x3a00
	s_waitcnt lgkmcnt(6)
	v_mfma_f32_32x32x16_bf16 v[48:63], v[148:151], v[112:115], v[48:63]
	ds_read_b64_tr_b16 v[148:149], v143 offset:0x400
	ds_read_b64_tr_b16 v[150:151], v143 offset:0xc00
	s_waitcnt lgkmcnt(6)
	v_mfma_f32_32x32x16_bf16 v[48:63], v[152:155], v[122:125], v[48:63]
	ds_read_b64_tr_b16 v[152:153], v143 offset:0x1400
	ds_read_b64_tr_b16 v[154:155], v143 offset:0x1c00
	s_waitcnt lgkmcnt(6)
; #define SBAR() __builtin_amdgcn_sched_barrier(0)
; template <int MLA>
; __device__ __forceinline__ void partialSM(f32x16& p0, f32x16& p1, float& m_reg, float& mn, float& alpha) {
;     ...
;   float pmax = p0[0];
; #pragma unroll
;   for (int r = 1; r < 16; ++r) pmax = fmaxf(pmax, p0[r]);
; #pragma unroll
;   for (int r = 0; r < 16; ++r) pmax = fmaxf(pmax, p1[r]);
;   { auto rr = __builtin_amdgcn_permlane32_swap(__float_as_uint(pmax), __float_as_uint(pmax), false, false);
;     pmax = fmaxf(__uint_as_float(rr[0]), __uint_as_float(rr[1])); }
;   if (__builtin_expect(__all(pmax - m_reg <= THR / SCALE), 1)) { mn = m_reg; alpha = 1.f; }
;   else { mn = fmaxf(m_reg, pmax); alpha = __builtin_amdgcn_exp2f((m_reg - mn) * C); m_reg = mn; }
; template <int D0> __device__ __forceinline__ void pv_one_t(f32x16& od, int vb, bf16x8 pa0, bf16x8 pa1, bf16x8 pa2, bf16x8 pa3) {
;   const s16x4 l0 = tr_read<v_rd_off(D0, 0, 0)>(vb), h0 = tr_read<v_rd_off(D0, 0, 1)>(vb), l1 = tr_read<v_rd_off(D0, 1, 0)>(vb), h1 = tr_read<v_rd_off(D0, 1, 1)>(vb);
;   const s16x4 l2 = tr_read<v_rd_off(D0, 2, 0)>(vb), h2 = tr_read<v_rd_off(D0, 2, 1)>(vb), l3 = tr_read<v_rd_off(D0, 3, 0)>(vb), h3 = tr_read<v_rd_off(D0, 3, 1)>(vb);
;   asm volatile("s_waitcnt lgkmcnt(0)" ::: "memory"); SBAR();
;     ...
;   od = __builtin_amdgcn_mfma_f32_32x32x16_bf16(PK(l0, h0), pa0, od, 0, 0, 0);
;   od = __builtin_amdgcn_mfma_f32_32x32x16_bf16(PK(l1, h1), pa1, od, 0, 0, 0);
;   od = __builtin_amdgcn_mfma_f32_32x32x16_bf16(PK(l2, h2), pa2, od, 0, 0, 0);
;   od = __builtin_amdgcn_mfma_f32_32x32x16_bf16(PK(l3, h3), pa3, od, 0, 0, 0);
;     ...
; }
	v_mfma_f32_32x32x16_bf16 v[48:63], v[170:173], v[126:129], v[48:63]
	ds_read_b64_tr_b16 v[170:171], v143 offset:0x2400
	ds_read_b64_tr_b16 v[172:173], v143 offset:0x2c00
	s_waitcnt lgkmcnt(6)
	v_mfma_f32_32x32x16_bf16 v[48:63], v[188:191], v[144:147], v[48:63]
	ds_read_b64_tr_b16 v[188:189], v143 offset:0x3400
	ds_read_b64_tr_b16 v[190:191], v143 offset:0x3c00
	s_waitcnt lgkmcnt(6)
	v_mfma_f32_32x32x16_bf16 v[16:31], v[148:151], v[112:115], v[16:31]
	ds_read_b64_tr_b16 v[148:149], v143 offset:0x600
	ds_read_b64_tr_b16 v[150:151], v143 offset:0xe00
	s_waitcnt lgkmcnt(6)
	v_mfma_f32_32x32x16_bf16 v[16:31], v[152:155], v[122:125], v[16:31]
	ds_read_b64_tr_b16 v[152:153], v143 offset:0x1600
	ds_read_b64_tr_b16 v[154:155], v143 offset:0x1e00
	s_waitcnt lgkmcnt(6)
	v_mfma_f32_32x32x16_bf16 v[16:31], v[170:173], v[126:129], v[16:31]
	ds_read_b64_tr_b16 v[170:171], v143 offset:0x2600
	ds_read_b64_tr_b16 v[172:173], v143 offset:0x2e00
	s_waitcnt lgkmcnt(6)
	v_mfma_f32_32x32x16_bf16 v[16:31], v[188:191], v[144:147], v[16:31]
	ds_read_b64_tr_b16 v[188:189], v143 offset:0x3600
	ds_read_b64_tr_b16 v[190:191], v143 offset:0x3e00
	s_waitcnt lgkmcnt(6)
	v_mfma_f32_32x32x16_bf16 v[0:15], v[148:151], v[112:115], v[0:15]
	v_max_f32_e32 v112, v80, v81
	v_max3_f32 v112, v112, v82, v83
	v_max3_f32 v112, v112, v84, v85
	v_max3_f32 v112, v112, v86, v87
	v_max3_f32 v112, v112, v88, v89
	v_max3_f32 v112, v112, v90, v91
	v_max3_f32 v112, v112, v92, v93
	s_waitcnt lgkmcnt(4)
	v_mfma_f32_32x32x16_bf16 v[0:15], v[152:155], v[122:125], v[0:15]
	v_max3_f32 v112, v112, v94, v95
	v_max3_f32 v112, v112, v64, v65
	v_max3_f32 v112, v112, v66, v67
	v_max3_f32 v112, v112, v68, v69
	v_max3_f32 v112, v112, v70, v71
	v_max3_f32 v112, v112, v72, v73
	v_max3_f32 v112, v112, v74, v75
	v_max3_f32 v112, v112, v76, v77
	s_waitcnt lgkmcnt(2)
	v_mfma_f32_32x32x16_bf16 v[0:15], v[170:173], v[126:129], v[0:15]
	v_max3_f32 v112, v112, v78, v79
	v_mov_b32_e32 v113, v112
	s_nop 1
	v_permlane32_swap_b32_e32 v112, v113
	v_max_f32_e32 v112, v112, v113
	v_cmp_ge_f32_e32 vcc, s70, v112
	s_waitcnt lgkmcnt(0)
	v_mfma_f32_32x32x16_bf16 v[0:15], v[188:191], v[144:147], v[0:15]
	s_cmp_eq_u64 vcc, exec
	s_cselect_b64 s[4:5], -1, 0
	s_waitcnt vmcnt(0) lgkmcnt(0)
	s_barrier
	s_cbranch_scc1 .Lal_c_d2
	v_max_f32_e32 v242, 0, v112
	v_exp_f32_e64 v112, -v242
	s_nop 0
	v_pk_mul_f32 v[46:47], v[46:47], v[112:113] op_sel_hi:[1,0]
	v_pk_mul_f32 v[44:45], v[44:45], v[112:113] op_sel_hi:[1,0]
	v_pk_mul_f32 v[42:43], v[42:43], v[112:113] op_sel_hi:[1,0]
	v_pk_mul_f32 v[40:41], v[40:41], v[112:113] op_sel_hi:[1,0]
	v_pk_mul_f32 v[38:39], v[38:39], v[112:113] op_sel_hi:[1,0]
	v_pk_mul_f32 v[36:37], v[36:37], v[112:113] op_sel_hi:[1,0]
	v_pk_mul_f32 v[34:35], v[34:35], v[112:113] op_sel_hi:[1,0]
	v_pk_mul_f32 v[32:33], v[32:33], v[112:113] op_sel_hi:[1,0]
	v_pk_mul_f32 v[62:63], v[62:63], v[112:113] op_sel_hi:[1,0]
	v_pk_mul_f32 v[60:61], v[60:61], v[112:113] op_sel_hi:[1,0]
	v_pk_mul_f32 v[58:59], v[58:59], v[112:113] op_sel_hi:[1,0]
	v_pk_mul_f32 v[56:57], v[56:57], v[112:113] op_sel_hi:[1,0]
	v_pk_mul_f32 v[54:55], v[54:55], v[112:113] op_sel_hi:[1,0]
	v_pk_mul_f32 v[52:53], v[52:53], v[112:113] op_sel_hi:[1,0]
	v_pk_mul_f32 v[50:51], v[50:51], v[112:113] op_sel_hi:[1,0]
	v_pk_mul_f32 v[48:49], v[48:49], v[112:113] op_sel_hi:[1,0]
	v_pk_mul_f32 v[30:31], v[30:31], v[112:113] op_sel_hi:[1,0]
	v_pk_mul_f32 v[28:29], v[28:29], v[112:113] op_sel_hi:[1,0]
	v_pk_mul_f32 v[26:27], v[26:27], v[112:113] op_sel_hi:[1,0]
	v_pk_mul_f32 v[24:25], v[24:25], v[112:113] op_sel_hi:[1,0]
	v_pk_mul_f32 v[22:23], v[22:23], v[112:113] op_sel_hi:[1,0]
	v_pk_mul_f32 v[20:21], v[20:21], v[112:113] op_sel_hi:[1,0]
	v_pk_mul_f32 v[18:19], v[18:19], v[112:113] op_sel_hi:[1,0]
	v_pk_mul_f32 v[16:17], v[16:17], v[112:113] op_sel_hi:[1,0]
	v_pk_mul_f32 v[14:15], v[14:15], v[112:113] op_sel_hi:[1,0]
	v_pk_mul_f32 v[12:13], v[12:13], v[112:113] op_sel_hi:[1,0]
	v_pk_mul_f32 v[10:11], v[10:11], v[112:113] op_sel_hi:[1,0]
	v_pk_mul_f32 v[8:9], v[8:9], v[112:113] op_sel_hi:[1,0]
	v_pk_mul_f32 v[6:7], v[6:7], v[112:113] op_sel_hi:[1,0]
	v_pk_mul_f32 v[4:5], v[4:5], v[112:113] op_sel_hi:[1,0]
	v_pk_mul_f32 v[2:3], v[2:3], v[112:113] op_sel_hi:[1,0]
	v_pk_mul_f32 v[0:1], v[0:1], v[112:113] op_sel_hi:[1,0]
	v_sub_f32_e32 v80, v80, v242
	v_sub_f32_e32 v81, v81, v242
	v_sub_f32_e32 v82, v82, v242
	v_sub_f32_e32 v83, v83, v242
	v_sub_f32_e32 v84, v84, v242
	v_sub_f32_e32 v85, v85, v242
	v_sub_f32_e32 v86, v86, v242
	v_sub_f32_e32 v87, v87, v242
	v_sub_f32_e32 v88, v88, v242
	v_sub_f32_e32 v89, v89, v242
	v_sub_f32_e32 v90, v90, v242
	v_sub_f32_e32 v91, v91, v242
	v_sub_f32_e32 v92, v92, v242
	v_sub_f32_e32 v93, v93, v242
	v_sub_f32_e32 v94, v94, v242
	v_sub_f32_e32 v95, v95, v242
	v_sub_f32_e32 v64, v64, v242
	v_sub_f32_e32 v65, v65, v242
	v_sub_f32_e32 v66, v66, v242
	v_sub_f32_e32 v67, v67, v242
	v_sub_f32_e32 v68, v68, v242
	v_sub_f32_e32 v69, v69, v242
	v_sub_f32_e32 v70, v70, v242
	v_sub_f32_e32 v71, v71, v242
	v_sub_f32_e32 v72, v72, v242
	v_sub_f32_e32 v73, v73, v242
	v_sub_f32_e32 v74, v74, v242
	v_sub_f32_e32 v75, v75, v242
	v_sub_f32_e32 v76, v76, v242
	v_sub_f32_e32 v77, v77, v242
	v_sub_f32_e32 v78, v78, v242
	v_sub_f32_e32 v79, v79, v242
	v_sub_f32_e32 v226, v226, v242
	v_sub_f32_e32 v227, v227, v242
	v_sub_f32_e32 v228, v228, v242
	v_sub_f32_e32 v229, v229, v242
	v_sub_f32_e32 v230, v230, v242
	v_sub_f32_e32 v231, v231, v242
	v_sub_f32_e32 v232, v232, v242
	v_sub_f32_e32 v233, v233, v242
	v_sub_f32_e32 v234, v234, v242
	v_sub_f32_e32 v235, v235, v242
	v_sub_f32_e32 v236, v236, v242
	v_sub_f32_e32 v237, v237, v242
	v_sub_f32_e32 v238, v238, v242
	v_sub_f32_e32 v239, v239, v242
	v_sub_f32_e32 v240, v240, v242
	v_sub_f32_e32 v241, v241, v242
	s_branch .LBB0_133
